# v081 + next tile's K fragment reads issued in the tile's tail (behind the last MFMA), QK starts right after the barrier
# speedup vs baseline: 1.0079x; 1.0004x over previous
; template <int N> __device__ __forceinline__ void wait_bar() { asm volatile("s_waitcnt vmcnt(%0) lgkmcnt(0)\n\ts_barrier" :: "n"(N) : "memory"); }
; #define AT_DMA(tr) do { const unsigned sb_ = (unsigned)__builtin_amdgcn_readfirstlane(dk + (((tr) & (NSTG - 1)) * STAGE)); const size_t ko_ = (size_t)(tr) * 26 * 4096, vo_ = (size_t)(tr) * 640 * 64; \
;         glds16(kg + ko_, sb_ + OFF_K0); if (!WIN) glds16(kg + ko_ + 4096, sb_ + OFF_K1); glds16(vg + vo_, sb_ + OFF_V); if (!WIN) glds16(vg + vo_ + 64 * 64, sb_ + OFF_V + 8192); } while (0)
; template <bool WIN> ...
;     ...
;         if (tr + 2 < NT) wait_bar<2 * NPW>(); else if (tr + 1 < NT) wait_bar<NPW>(); else wait_bar<0>();
;         if (tr + 3 < NT) AT_DMA(tr + 3);
;         const int k0 = (t_lo + tr) * 64;
;         const bool skip = WIN && (k0 > qw + 31 + 128 || k0 + 63 < qw - 128);
;         if (!skip) {
;             const bool near = WIN || ((k0 - (qw + 31)) < 128 && (qw - (k0 + 63)) < 128);
;             const float cinit = near ? 0.f : (k0 > qw ? cfar_hi : cfar_lo);
;             if (__builtin_expect(cinit != cbase, 0)) { cbase = cinit; asm volatile("" ::: "memory");
.LSPp_top:
	s_cmpk_gt_u32 s86, 124
	s_cbranch_scc1 .LSPp_slowtop
	s_waitcnt vmcnt(4) lgkmcnt(0)
	s_barrier
	s_mov_b32 s64, s65
	s_cmp_eq_u32 m0, s100
	s_cbranch_scc0 .LSPp_cin

; #define ALAS __attribute__((address_space(3)))
; #define AT_DMA(tr) do { const unsigned sb_ = (unsigned)__builtin_amdgcn_readfirstlane(dk + (((tr) & (NSTG - 1)) * STAGE)); const size_t ko_ = (size_t)(tr) * 26 * 4096, vo_ = (size_t)(tr) * 640 * 64; \
;         glds16(kg + ko_, sb_ + OFF_K0); if (!WIN) glds16(kg + ko_ + 4096, sb_ + OFF_K1); glds16(vg + vo_, sb_ + OFF_V); if (!WIN) glds16(vg + vo_ + 64 * 64, sb_ + OFF_V + 8192); } while (0)
; template <bool WIN> ...
;     ...
;         if (tr + 3 < NT) AT_DMA(tr + 3);
;     ...
;                 bf16x8 ka[8];
; #pragma unroll
;                 for (int ds = 0; ds < 4; ++ds) { ka[2 * ds] = *(const ALAS bf16x8*)(sb + kx[ds]); ka[2 * ds + 1] = *(const ALAS bf16x8*)(sb + kx[ds] + 4096); }
;                 __builtin_amdgcn_sched_barrier(0);
;                 s0 = __builtin_amdgcn_mfma_f32_32x32x16_bf16(ka[0], qf(0), cvec, 0, 0, 0);
;                 s1 = __builtin_amdgcn_mfma_f32_32x32x16_bf16(ka[1], qf(0), cvec, 0, 0, 0);
; #pragma unroll
;                 for (int ds = 1; ds < 4; ++ds) {
;                     s0 = __builtin_amdgcn_mfma_f32_32x32x16_bf16(ka[2 * ds], qf(ds), s0, 0, 0, 0);
;                     s1 = __builtin_amdgcn_mfma_f32_32x32x16_bf16(ka[2 * ds + 1], qf(ds), s1, 0, 0, 0);
;                 }
;             }
.LSPp_k0bk:
	s_mov_b32 m0, s98
	v_mfma_f32_32x32x16_bf16 v[98:113], v[130:133], v[126:129], v[66:81]
	global_load_lds_dwordx4 v[174:175], off
	s_add_i32 m0, s98, 0x2000
	v_mfma_f32_32x32x16_bf16 v[82:97], v[134:137], v[126:129], v[66:81]
	global_load_lds_dwordx4 v[208:209], off
	s_add_i32 m0, s101, 0x4000
	v_mfma_f32_32x32x16_bf16 v[98:113], v[138:141], v[122:125], v[98:113]
	global_load_lds_dwordx4 v[172:173], off
	s_add_i32 m0, s101, 0x6000
	v_mfma_f32_32x32x16_bf16 v[82:97], v[142:145], v[122:125], v[82:97]
	global_load_lds_dwordx4 v[210:211], off
	v_mfma_f32_32x32x16_bf16 v[98:113], v[146:149], v[118:121], v[98:113]
	v_mfma_f32_32x32x16_bf16 v[82:97], v[150:153], v[118:121], v[82:97]
	v_mfma_f32_32x32x16_bf16 v[98:113], v[158:161], v[114:117], v[98:113]
	v_mfma_f32_32x32x16_bf16 v[82:97], v[204:207], v[114:117], v[82:97]

; #define ALAS __attribute__((address_space(3)))
; template <bool WIN> ...
;     ...
;             const bool near = WIN || ((k0 - (qw + 31)) < 128 && (qw - (k0 + 63)) < 128);
;             const float cinit = near ? 0.f : (k0 > qw ? cfar_hi : cfar_lo);
;     ...
;             union PFU { u32x4 u; bf16x8 b; };
;             PFU p0, p1, p2, p3;
;             AT_EXP(s0, 0, p0);
; #pragma unroll
;             for (int kk = 0; kk < 2; ++kk)
; #pragma unroll
;                 for (int db = 0; db < NDB; ++db) vc[kk * NDB + db] = *(const ALAS bf16x8*)(sb + vx[kk + 2] + db * 4096);
;             __builtin_amdgcn_sched_barrier(0);
; #pragma unroll
;             for (int db = 0; db < NDB; ++db) o[db] = __builtin_amdgcn_mfma_f32_32x32x16_bf16(va[db], p0.b, o[db], 0, 0, 0);
;             AT_EXP(s0, 8, p1);
;             __builtin_amdgcn_sched_barrier(0);
; #pragma unroll
;             for (int db = 0; db < NDB; ++db) o[db] = __builtin_amdgcn_mfma_f32_32x32x16_bf16(va[NDB + db], p1.b, o[db], 0, 0, 0);
;             AT_EXP(s1, 0, p2);
;             __builtin_amdgcn_sched_barrier(0);
; #pragma unroll
;             for (int db = 0; db < NDB; ++db) o[db] = __builtin_amdgcn_mfma_f32_32x32x16_bf16(vc[db], p2.b, o[db], 0, 0, 0);
;             AT_EXP(s1, 8, p3);
;             __builtin_amdgcn_sched_barrier(0);
; #pragma unroll
;             for (int db = 0; db < NDB; ++db) o[db] = __builtin_amdgcn_mfma_f32_32x32x16_bf16(vc[NDB + db], p3.b, o[db], 0, 0, 0);
;             __builtin_amdgcn_sched_barrier(0);
;     ...
;             l_run += ls0 + ls1;
.LSPp_pv:
	s_cmp_eq_u32 s86, 0
	s_cbranch_scc1 .LSPp_pure
	s_waitcnt lgkmcnt(4)
	v_mfma_f32_32x32x16_bf16 v[50:65], v[146:149], v[238:241], v[50:65]
	v_exp_f32_e32 v98, v98
	v_exp_f32_e32 v99, v99
	v_mfma_f32_32x32x16_bf16 v[34:49], v[150:153], v[238:241], v[34:49]
	v_exp_f32_e32 v100, v100
	v_exp_f32_e32 v101, v101
	v_mfma_f32_32x32x16_bf16 v[18:33], v[154:157], v[238:241], v[18:33]
	v_exp_f32_e32 v102, v102
	v_exp_f32_e32 v103, v103
	v_add_f32_e32 v228, v98, v100
	v_add_f32_e32 v229, v99, v101
	v_mfma_f32_32x32x16_bf16 v[2:17], v[158:161], v[238:241], v[2:17]
	v_exp_f32_e32 v104, v104
	v_exp_f32_e32 v105, v105
	v_add_f32_e32 v228, v228, v102
	v_add_f32_e32 v229, v229, v103
	v_add3_u32 v236, s99, v183, v187
	ds_read_b128 v[146:149], v236 offset:16384
	ds_read_b128 v[150:153], v236 offset:20480
	ds_read_b128 v[154:157], v236 offset:24576
	ds_read_b128 v[158:161], v236 offset:28672
	s_waitcnt lgkmcnt(4)
	v_mfma_f32_32x32x16_bf16 v[50:65], v[130:133], v[242:245], v[50:65]
	v_exp_f32_e32 v106, v106
	v_exp_f32_e32 v107, v107
	v_add_f32_e32 v228, v228, v104
	v_add_f32_e32 v229, v229, v105
	v_cvt_pk_bf16_f32 v238, v98, v99
	v_lshl_add_u64 v[174:175], v[174:175], 0, s[60:61]
	s_add_i32 s87, s85, 0xffff8000
	s_and_b32 s87, s87, 0x18000
	v_mfma_f32_32x32x16_bf16 v[34:49], v[134:137], v[242:245], v[34:49]
	v_exp_f32_e32 v108, v108
	v_exp_f32_e32 v109, v109
	v_add_f32_e32 v228, v228, v106
	v_add_f32_e32 v229, v229, v107
	v_cvt_pk_bf16_f32 v239, v100, v101
	v_lshl_add_u64 v[172:173], v[172:173], 0, s[48:49]
	s_add_i32 s98, s85, 0x10000
	s_and_b32 s98, s98, 0x18000
	v_mfma_f32_32x32x16_bf16 v[18:33], v[138:141], v[242:245], v[18:33]
	v_exp_f32_e32 v110, v110
	v_exp_f32_e32 v111, v111
	v_add_f32_e32 v228, v228, v108
	v_add_f32_e32 v229, v229, v109
	v_cvt_pk_bf16_f32 v240, v102, v103
	v_lshl_add_u64 v[208:209], v[174:175], 0, s[40:41]
	s_add_i32 s98, s98, s20
	s_add_i32 s101, s85, 0x8000
	v_mfma_f32_32x32x16_bf16 v[2:17], v[142:145], v[242:245], v[2:17]
	v_exp_f32_e32 v112, v112
	v_exp_f32_e32 v113, v113
	v_add_f32_e32 v228, v228, v110
	v_add_f32_e32 v229, v229, v111
	v_cvt_pk_bf16_f32 v241, v104, v105
	v_lshl_add_u64 v[210:211], v[172:173], 0, s[40:41]
	s_and_b32 s101, s101, 0x18000
	s_add_i32 s101, s101, s20
	v_add3_u32 v237, s99, v190, v187
	ds_read_b128 v[130:133], v237 offset:16384
	ds_read_b128 v[134:137], v237 offset:20480
	ds_read_b128 v[138:141], v237 offset:24576
	ds_read_b128 v[142:145], v237 offset:28672
	s_waitcnt lgkmcnt(4)
	v_mfma_f32_32x32x16_bf16 v[50:65], v[146:149], v[246:249], v[50:65]
	v_exp_f32_e32 v82, v82
	v_exp_f32_e32 v83, v83
	v_add_f32_e32 v228, v228, v112
	v_add_f32_e32 v229, v229, v113
	v_cvt_pk_bf16_f32 v242, v106, v107
	v_add3_u32 v212, s87, v178, v162
	s_add_i32 s99, s81, s83
	s_add_i32 s99, s99, 64
	v_mfma_f32_32x32x16_bf16 v[34:49], v[150:153], v[246:249], v[34:49]
	v_exp_f32_e32 v84, v84
	v_exp_f32_e32 v85, v85
	v_add_f32_e32 v228, v228, v82
	v_add_f32_e32 v229, v229, v83
	v_cvt_pk_bf16_f32 v243, v108, v109
	v_add3_u32 v213, s87, v180, v162
	s_sub_i32 m0, s82, 64
	s_max_i32 s99, s99, m0
	v_mfma_f32_32x32x16_bf16 v[18:33], v[154:157], v[246:249], v[18:33]
	v_exp_f32_e32 v86, v86
	v_exp_f32_e32 v87, v87
	v_add_f32_e32 v228, v228, v84
	v_add_f32_e32 v229, v229, v85
	v_cvt_pk_bf16_f32 v244, v110, v111
	v_add3_u32 v214, s87, v182, v162
	s_add_i32 m0, s83, 64
	s_cmp_gt_i32 m0, s78
	v_mfma_f32_32x32x16_bf16 v[2:17], v[158:161], v[246:249], v[2:17]
	v_exp_f32_e32 v88, v88
	v_exp_f32_e32 v89, v89
	v_add_f32_e32 v228, v228, v86
	v_add_f32_e32 v229, v229, v87
	v_cvt_pk_bf16_f32 v245, v112, v113
	v_add3_u32 v215, s87, v184, v162
	s_cselect_b32 m0, s80, s79
	s_cmpk_lt_i32 s99, 0x80
	s_waitcnt lgkmcnt(0)
	v_mfma_f32_32x32x16_bf16 v[50:65], v[130:133], v[250:253], v[50:65]
	v_exp_f32_e32 v90, v90
	v_exp_f32_e32 v91, v91
	v_add_f32_e32 v228, v228, v88
	v_add_f32_e32 v229, v229, v89
	v_cvt_pk_bf16_f32 v246, v82, v83
	s_cselect_b32 s65, 1, 0
	s_cselect_b32 m0, 0, m0
	v_mfma_f32_32x32x16_bf16 v[34:49], v[134:137], v[250:253], v[34:49]
	v_exp_f32_e32 v92, v92
	v_exp_f32_e32 v93, v93
	v_add_f32_e32 v228, v228, v90
	v_add_f32_e32 v229, v229, v91
	v_cvt_pk_bf16_f32 v247, v84, v85
	s_add_i32 s99, s85, 0xffff0000
	s_and_b32 s99, s99, 0x18000
	v_mfma_f32_32x32x16_bf16 v[18:33], v[138:141], v[250:253], v[18:33]
	v_exp_f32_e32 v94, v94
	v_exp_f32_e32 v95, v95
	v_add_f32_e32 v228, v228, v92
	v_add_f32_e32 v229, v229, v93
	v_cvt_pk_bf16_f32 v248, v86, v87
	v_mfma_f32_32x32x16_bf16 v[2:17], v[142:145], v[250:253], v[2:17]
	v_exp_f32_e32 v96, v96
	v_exp_f32_e32 v97, v97
	v_add_f32_e32 v228, v228, v94
	v_add_f32_e32 v229, v229, v95
	v_cvt_pk_bf16_f32 v249, v88, v89
	v_add_f32_e32 v228, v228, v96
	v_add_f32_e32 v229, v229, v97
	v_cvt_pk_bf16_f32 v250, v90, v91
	v_cvt_pk_bf16_f32 v251, v92, v93
	v_cvt_pk_bf16_f32 v252, v94, v95
	v_cvt_pk_bf16_f32 v253, v96, v97
	ds_read_b128 v[130:133], v212
	ds_read_b128 v[134:137], v212 offset:4096
	ds_read_b128 v[138:141], v213
	ds_read_b128 v[142:145], v213 offset:4096
	ds_read_b128 v[146:149], v214
	ds_read_b128 v[150:153], v214 offset:4096
	ds_read_b128 v[158:161], v215
	ds_read_b128 v[204:207], v215 offset:4096
	v_add_f32_e32 v228, v228, v229
	v_cmp_nge_f32_e32 vcc, 0x53800000, v228
	s_cbranch_vccnz .LSPp_redo
	s_add_i32 s86, s86, 1
	s_add_i32 s85, s85, 0x8000
	s_addk_i32 s84, 0x100
	s_add_i32 s83, s83, 64
	s_sub_i32 s82, s82, 64
	v_add_f32_e32 v0, v0, v228
	s_cmpk_eq_u32 s84, 0x8000
	s_cbranch_scc0 .LSPp_top
	s_branch .LSPp_exit
; #define ALAS __attribute__((address_space(3)))
; template <bool WIN> ...
;     ...
;             union PFU { u32x4 u; bf16x8 b; };
;             PFU p0, p1, p2, p3;
;             AT_EXP(s0, 0, p0);
; #pragma unroll
;             for (int kk = 0; kk < 2; ++kk)
; #pragma unroll
;                 for (int db = 0; db < NDB; ++db) vc[kk * NDB + db] = *(const ALAS bf16x8*)(sb + vx[kk + 2] + db * 4096);
;             __builtin_amdgcn_sched_barrier(0);
; #pragma unroll
;             for (int db = 0; db < NDB; ++db) o[db] = __builtin_amdgcn_mfma_f32_32x32x16_bf16(va[db], p0.b, o[db], 0, 0, 0);
;             AT_EXP(s0, 8, p1);
;             __builtin_amdgcn_sched_barrier(0);
; #pragma unroll
;             for (int db = 0; db < NDB; ++db) o[db] = __builtin_amdgcn_mfma_f32_32x32x16_bf16(va[NDB + db], p1.b, o[db], 0, 0, 0);
;             AT_EXP(s1, 0, p2);
;             __builtin_amdgcn_sched_barrier(0);
; #pragma unroll
;             for (int db = 0; db < NDB; ++db) o[db] = __builtin_amdgcn_mfma_f32_32x32x16_bf16(vc[db], p2.b, o[db], 0, 0, 0);
;             AT_EXP(s1, 8, p3);
;             __builtin_amdgcn_sched_barrier(0);
; #pragma unroll
;             for (int db = 0; db < NDB; ++db) o[db] = __builtin_amdgcn_mfma_f32_32x32x16_bf16(vc[NDB + db], p3.b, o[db], 0, 0, 0);
;             __builtin_amdgcn_sched_barrier(0);
;     ...
;             l_run += ls0 + ls1;
.LSPp_pure:
	v_lshl_add_u64 v[174:175], v[174:175], 0, s[60:61]
	v_lshl_add_u64 v[172:173], v[172:173], 0, s[48:49]
	s_add_i32 s98, s85, 0x10000
	s_and_b32 s98, s98, 0x18000
	s_add_i32 s98, s98, s20
	s_add_i32 s101, s85, 0x8000
	s_and_b32 s101, s101, 0x18000
	s_add_i32 s101, s101, s20
	v_lshl_add_u64 v[208:209], v[174:175], 0, s[40:41]
	v_lshl_add_u64 v[210:211], v[172:173], 0, s[40:41]
	s_add_i32 s87, s85, 0xffff8000
	s_and_b32 s87, s87, 0x18000
	v_add3_u32 v212, s87, v178, v162
	v_add3_u32 v213, s87, v180, v162
	v_add3_u32 v214, s87, v182, v162
	v_add3_u32 v215, s87, v184, v162
	s_add_i32 s99, s81, s83
	s_add_i32 s99, s99, 64
	s_sub_i32 m0, s82, 64
	s_max_i32 s99, s99, m0
	s_add_i32 m0, s83, 64
	s_cmp_gt_i32 m0, s78
	s_cselect_b32 m0, s80, s79
	s_cmpk_lt_i32 s99, 0x80
	s_cselect_b32 s65, 1, 0
	s_cselect_b32 m0, 0, m0
	s_add_i32 s99, s85, 0xffff0000
	s_and_b32 s99, s99, 0x18000
	v_exp_f32_e32 v98, v98
	v_exp_f32_e32 v99, v99
	v_exp_f32_e32 v100, v100
	v_exp_f32_e32 v101, v101
	v_exp_f32_e32 v102, v102
	v_exp_f32_e32 v103, v103
	v_exp_f32_e32 v104, v104
	v_exp_f32_e32 v105, v105
	v_cvt_pk_bf16_f32 v238, v98, v99
	v_cvt_pk_bf16_f32 v239, v100, v101
	v_cvt_pk_bf16_f32 v240, v102, v103
	v_cvt_pk_bf16_f32 v241, v104, v105
	v_mov_b32_e32 v228, v98
	v_mov_b32_e32 v229, v102
	v_add_f32_e32 v228, v228, v99
	v_add_f32_e32 v229, v229, v103
	v_add_f32_e32 v228, v228, v100
	v_add_f32_e32 v229, v229, v104
	v_add_f32_e32 v228, v228, v101
	v_add_f32_e32 v229, v229, v105
	v_exp_f32_e32 v106, v106
	v_exp_f32_e32 v107, v107
	v_exp_f32_e32 v108, v108
	v_exp_f32_e32 v109, v109
	v_exp_f32_e32 v110, v110
	v_exp_f32_e32 v111, v111
	v_exp_f32_e32 v112, v112
	v_exp_f32_e32 v113, v113
	v_cvt_pk_bf16_f32 v242, v106, v107
	v_cvt_pk_bf16_f32 v243, v108, v109
	v_cvt_pk_bf16_f32 v244, v110, v111
	v_cvt_pk_bf16_f32 v245, v112, v113
	v_add_f32_e32 v228, v228, v106
	v_add_f32_e32 v229, v229, v110
	v_add_f32_e32 v228, v228, v107
	v_add_f32_e32 v229, v229, v111
	v_add_f32_e32 v228, v228, v108
	v_add_f32_e32 v229, v229, v112
	v_add_f32_e32 v228, v228, v109
	v_add_f32_e32 v229, v229, v113
	v_exp_f32_e32 v82, v82
	v_exp_f32_e32 v83, v83
	v_exp_f32_e32 v84, v84
	v_exp_f32_e32 v85, v85
	v_exp_f32_e32 v86, v86
	v_exp_f32_e32 v87, v87
	v_exp_f32_e32 v88, v88
	v_exp_f32_e32 v89, v89
	v_cvt_pk_bf16_f32 v246, v82, v83
	v_cvt_pk_bf16_f32 v247, v84, v85
	v_cvt_pk_bf16_f32 v248, v86, v87
	v_cvt_pk_bf16_f32 v249, v88, v89
	v_add_f32_e32 v228, v228, v82
	v_add_f32_e32 v229, v229, v86
	v_add_f32_e32 v228, v228, v83
	v_add_f32_e32 v229, v229, v87
	v_add_f32_e32 v228, v228, v84
	v_add_f32_e32 v229, v229, v88
	v_add_f32_e32 v228, v228, v85
	v_add_f32_e32 v229, v229, v89
	v_exp_f32_e32 v90, v90
	v_exp_f32_e32 v91, v91
	v_exp_f32_e32 v92, v92
	v_exp_f32_e32 v93, v93
	v_exp_f32_e32 v94, v94
	v_exp_f32_e32 v95, v95
	v_exp_f32_e32 v96, v96
	v_exp_f32_e32 v97, v97
	v_cvt_pk_bf16_f32 v250, v90, v91
	v_cvt_pk_bf16_f32 v251, v92, v93
	v_cvt_pk_bf16_f32 v252, v94, v95
	v_cvt_pk_bf16_f32 v253, v96, v97
	v_add_f32_e32 v228, v228, v90
	v_add_f32_e32 v229, v229, v94
	v_add_f32_e32 v228, v228, v91
	v_add_f32_e32 v229, v229, v95
	v_add_f32_e32 v228, v228, v92
	v_add_f32_e32 v229, v229, v96
	v_add_f32_e32 v228, v228, v93
	v_add_f32_e32 v229, v229, v97
	ds_read_b128 v[130:133], v212
	ds_read_b128 v[134:137], v212 offset:4096
	ds_read_b128 v[138:141], v213
	ds_read_b128 v[142:145], v213 offset:4096
	ds_read_b128 v[146:149], v214
	ds_read_b128 v[150:153], v214 offset:4096
	ds_read_b128 v[158:161], v215
	ds_read_b128 v[204:207], v215 offset:4096
	v_add_f32_e32 v228, v228, v229
	v_cmp_nge_f32_e32 vcc, 0x53800000, v228
	s_cbranch_vccnz .LSPp_redo
	s_add_i32 s86, s86, 1
	s_add_i32 s85, s85, 0x8000
	s_addk_i32 s84, 0x100
	s_add_i32 s83, s83, 64
	s_sub_i32 s82, s82, 64
	v_add_f32_e32 v0, v0, v228
	s_cmpk_eq_u32 s84, 0x8000
	s_cbranch_scc0 .LSPp_top
	s_branch .LSPp_exit

; #define ALAS __attribute__((address_space(3)))
; template <bool WIN> ...
;     ...
;             union PFU { u32x4 u; bf16x8 b; };
;             PFU p0, p1, p2, p3;
;             AT_EXP(s0, 0, p0);
; #pragma unroll
;             for (int kk = 0; kk < 2; ++kk)
; #pragma unroll
;                 for (int db = 0; db < NDB; ++db) vc[kk * NDB + db] = *(const ALAS bf16x8*)(sb + vx[kk + 2] + db * 4096);
;             __builtin_amdgcn_sched_barrier(0);
; #pragma unroll
;             for (int db = 0; db < NDB; ++db) o[db] = __builtin_amdgcn_mfma_f32_32x32x16_bf16(va[db], p0.b, o[db], 0, 0, 0);
;             AT_EXP(s0, 8, p1);
;             __builtin_amdgcn_sched_barrier(0);
; #pragma unroll
;             for (int db = 0; db < NDB; ++db) o[db] = __builtin_amdgcn_mfma_f32_32x32x16_bf16(va[NDB + db], p1.b, o[db], 0, 0, 0);
;             AT_EXP(s1, 0, p2);
;             __builtin_amdgcn_sched_barrier(0);
; #pragma unroll
;             for (int db = 0; db < NDB; ++db) o[db] = __builtin_amdgcn_mfma_f32_32x32x16_bf16(vc[db], p2.b, o[db], 0, 0, 0);
;             AT_EXP(s1, 8, p3);
;             __builtin_amdgcn_sched_barrier(0);
; #pragma unroll
;             for (int db = 0; db < NDB; ++db) o[db] = __builtin_amdgcn_mfma_f32_32x32x16_bf16(vc[NDB + db], p3.b, o[db], 0, 0, 0);
;             __builtin_amdgcn_sched_barrier(0);
;     ...
;             l_run += ls0 + ls1;
.LSPp_pure2:
	s_add_i32 s87, s85, 0xffff8000
	s_and_b32 s87, s87, 0x18000
	v_lshl_add_u64 v[208:209], v[174:175], 0, s[40:41]
	v_lshl_add_u64 v[210:211], v[172:173], 0, s[40:41]
	v_add3_u32 v212, s87, v178, v162
	v_add3_u32 v213, s87, v180, v162
	v_add3_u32 v214, s87, v182, v162
	v_add3_u32 v215, s87, v184, v162
	v_exp_f32_e32 v98, v98
	v_exp_f32_e32 v99, v99
	v_exp_f32_e32 v100, v100
	v_exp_f32_e32 v101, v101
	v_exp_f32_e32 v102, v102
	v_exp_f32_e32 v103, v103
	v_exp_f32_e32 v104, v104
	v_exp_f32_e32 v105, v105
	v_cvt_pk_bf16_f32 v238, v98, v99
	v_cvt_pk_bf16_f32 v239, v100, v101
	v_cvt_pk_bf16_f32 v240, v102, v103
	v_cvt_pk_bf16_f32 v241, v104, v105
	v_mov_b32_e32 v228, v98
	v_mov_b32_e32 v229, v102
	v_add_f32_e32 v228, v228, v99
	v_add_f32_e32 v229, v229, v103
	v_add_f32_e32 v228, v228, v100
	v_add_f32_e32 v229, v229, v104
	v_add_f32_e32 v228, v228, v101
	v_add_f32_e32 v229, v229, v105
	v_exp_f32_e32 v106, v106
	v_exp_f32_e32 v107, v107
	v_exp_f32_e32 v108, v108
	v_exp_f32_e32 v109, v109
	v_exp_f32_e32 v110, v110
	v_exp_f32_e32 v111, v111
	v_exp_f32_e32 v112, v112
	v_exp_f32_e32 v113, v113
	v_cvt_pk_bf16_f32 v242, v106, v107
	v_cvt_pk_bf16_f32 v243, v108, v109
	v_cvt_pk_bf16_f32 v244, v110, v111
	v_cvt_pk_bf16_f32 v245, v112, v113
	v_add_f32_e32 v228, v228, v106
	v_add_f32_e32 v229, v229, v110
	v_add_f32_e32 v228, v228, v107
	v_add_f32_e32 v229, v229, v111
	v_add_f32_e32 v228, v228, v108
	v_add_f32_e32 v229, v229, v112
	v_add_f32_e32 v228, v228, v109
	v_add_f32_e32 v229, v229, v113
	v_exp_f32_e32 v82, v82
	v_exp_f32_e32 v83, v83
	v_exp_f32_e32 v84, v84
	v_exp_f32_e32 v85, v85
	v_exp_f32_e32 v86, v86
	v_exp_f32_e32 v87, v87
	v_exp_f32_e32 v88, v88
	v_exp_f32_e32 v89, v89
	v_cvt_pk_bf16_f32 v246, v82, v83
	v_cvt_pk_bf16_f32 v247, v84, v85
	v_cvt_pk_bf16_f32 v248, v86, v87
	v_cvt_pk_bf16_f32 v249, v88, v89
	v_add_f32_e32 v228, v228, v82
	v_add_f32_e32 v229, v229, v86
	v_add_f32_e32 v228, v228, v83
	v_add_f32_e32 v229, v229, v87
	v_add_f32_e32 v228, v228, v84
	v_add_f32_e32 v229, v229, v88
	v_add_f32_e32 v228, v228, v85
	v_add_f32_e32 v229, v229, v89
	v_exp_f32_e32 v90, v90
	v_exp_f32_e32 v91, v91
	v_exp_f32_e32 v92, v92
	v_exp_f32_e32 v93, v93
	v_exp_f32_e32 v94, v94
	v_exp_f32_e32 v95, v95
	v_exp_f32_e32 v96, v96
	v_exp_f32_e32 v97, v97
	v_cvt_pk_bf16_f32 v250, v90, v91
	v_cvt_pk_bf16_f32 v251, v92, v93
	v_cvt_pk_bf16_f32 v252, v94, v95
	v_cvt_pk_bf16_f32 v253, v96, v97
	v_add_f32_e32 v228, v228, v90
	v_add_f32_e32 v229, v229, v94
	v_add_f32_e32 v228, v228, v91
	v_add_f32_e32 v229, v229, v95
	v_add_f32_e32 v228, v228, v92
	v_add_f32_e32 v229, v229, v96
	v_add_f32_e32 v228, v228, v93
	v_add_f32_e32 v229, v229, v97
	ds_read_b128 v[130:133], v212
	ds_read_b128 v[134:137], v212 offset:4096
	ds_read_b128 v[138:141], v213
	ds_read_b128 v[142:145], v213 offset:4096
	ds_read_b128 v[146:149], v214
	ds_read_b128 v[150:153], v214 offset:4096
	ds_read_b128 v[158:161], v215
	ds_read_b128 v[204:207], v215 offset:4096
	v_add_f32_e32 v228, v228, v229
	s_add_i32 s86, s86, 1
	s_add_i32 s85, s85, 0x8000
	s_addk_i32 s84, 0x100
	s_add_i32 s83, s83, 64
	s_sub_i32 s82, s82, 64
	v_add_f32_e32 v0, v0, v228
	s_cmpk_eq_u32 s84, 0x8000
	s_cbranch_scc0 .LSPp_top
	s_branch .LSPp_exit

; #define ALAS __attribute__((address_space(3)))
; template <bool WIN> ...
;     ...
;                 bf16x8 ka[8];
; #pragma unroll
;                 for (int ds = 0; ds < 4; ++ds) { ka[2 * ds] = *(const ALAS bf16x8*)(sb + kx[ds]); ka[2 * ds + 1] = *(const ALAS bf16x8*)(sb + kx[ds] + 4096); }
;                 __builtin_amdgcn_sched_barrier(0);
.LSPp_k0rd:
	ds_read_b128 v[130:133], v212
	ds_read_b128 v[134:137], v212 offset:4096
	ds_read_b128 v[138:141], v213
	ds_read_b128 v[142:145], v213 offset:4096
	ds_read_b128 v[146:149], v214
	ds_read_b128 v[150:153], v214 offset:4096
	ds_read_b128 v[158:161], v215
	ds_read_b128 v[204:207], v215 offset:4096
	s_waitcnt lgkmcnt(0)
	s_branch .LSPp_k0bk

; #define ALAS __attribute__((address_space(3)))
; template <bool WIN> ...
;     ...
;                 bf16x8 ka[8];
; #pragma unroll
;                 for (int ds = 0; ds < 4; ++ds) { ka[2 * ds] = *(const ALAS bf16x8*)(sb + kx[ds]); ka[2 * ds + 1] = *(const ALAS bf16x8*)(sb + kx[ds] + 4096); }
;                 __builtin_amdgcn_sched_barrier(0);
;                 s0 = __builtin_amdgcn_mfma_f32_32x32x16_bf16(ka[0], qf(0), cvec, 0, 0, 0);
;                 s1 = __builtin_amdgcn_mfma_f32_32x32x16_bf16(ka[1], qf(0), cvec, 0, 0, 0);
; #pragma unroll
;                 for (int ds = 1; ds < 4; ++ds) {
;                     s0 = __builtin_amdgcn_mfma_f32_32x32x16_bf16(ka[2 * ds], qf(ds), s0, 0, 0, 0);
;                     s1 = __builtin_amdgcn_mfma_f32_32x32x16_bf16(ka[2 * ds + 1], qf(ds), s1, 0, 0, 0);
;                 }
;             }
.LSPp_skipv:
	v_mfma_f32_32x32x16_bf16 v[98:113], v[130:133], v[126:129], v[66:81]
	v_mfma_f32_32x32x16_bf16 v[82:97], v[134:137], v[126:129], v[66:81]
	v_mfma_f32_32x32x16_bf16 v[98:113], v[138:141], v[122:125], v[98:113]
	v_mfma_f32_32x32x16_bf16 v[82:97], v[142:145], v[122:125], v[82:97]
	v_mfma_f32_32x32x16_bf16 v[98:113], v[146:149], v[118:121], v[98:113]
	v_mfma_f32_32x32x16_bf16 v[82:97], v[150:153], v[118:121], v[82:97]
	v_mfma_f32_32x32x16_bf16 v[98:113], v[158:161], v[114:117], v[98:113]
	v_mfma_f32_32x32x16_bf16 v[82:97], v[204:207], v[114:117], v[82:97]
	s_branch .LSPp_vrd

; template <int N> __device__ __forceinline__ void wait_bar() { asm volatile("s_waitcnt vmcnt(%0) lgkmcnt(0)\n\ts_barrier" :: "n"(N) : "memory"); }
; #define AT_DMA(tr) do { const unsigned sb_ = (unsigned)__builtin_amdgcn_readfirstlane(dk + (((tr) & (NSTG - 1)) * STAGE)); const size_t ko_ = (size_t)(tr) * 26 * 4096, vo_ = (size_t)(tr) * 640 * 64; \
;         glds16(kg + ko_, sb_ + OFF_K0); if (!WIN) glds16(kg + ko_ + 4096, sb_ + OFF_K1); glds16(vg + vo_, sb_ + OFF_V); if (!WIN) glds16(vg + vo_ + 64 * 64, sb_ + OFF_V + 8192); } while (0)
; template <bool WIN> ...
;     ...
;         if (tr + 2 < NT) wait_bar<2 * NPW>(); else if (tr + 1 < NT) wait_bar<NPW>(); else wait_bar<0>();
;         if (tr + 3 < NT) AT_DMA(tr + 3);
;         const int k0 = (t_lo + tr) * 64;
;         const bool skip = WIN && (k0 > qw + 31 + 128 || k0 + 63 < qw - 128);
;         if (!skip) {
;             const bool near = WIN || ((k0 - (qw + 31)) < 128 && (qw - (k0 + 63)) < 128);
;             const float cinit = near ? 0.f : (k0 > qw ? cfar_hi : cfar_lo);
;             if (__builtin_expect(cinit != cbase, 0)) { cbase = cinit; asm volatile("" ::: "memory");
.LSPs_top:
	s_cmpk_gt_u32 s79, 28
	s_cbranch_scc1 .LSPs_slowtop
	s_waitcnt vmcnt(4) lgkmcnt(0)
	s_barrier
	s_mov_b32 s64, s65
	s_cmp_eq_u32 m0, s100
	s_cbranch_scc0 .LSPs_cin

; #define ALAS __attribute__((address_space(3)))
; template <bool WIN> ...
;     ...
;             const bool near = WIN || ((k0 - (qw + 31)) < 128 && (qw - (k0 + 63)) < 128);
;             const float cinit = near ? 0.f : (k0 > qw ? cfar_hi : cfar_lo);
;     ...
;             union PFU { u32x4 u; bf16x8 b; };
;             PFU p0, p1, p2, p3;
;             AT_EXP(s0, 0, p0);
; #pragma unroll
;             for (int kk = 0; kk < 2; ++kk)
; #pragma unroll
;                 for (int db = 0; db < NDB; ++db) vc[kk * NDB + db] = *(const ALAS bf16x8*)(sb + vx[kk + 2] + db * 4096);
;             __builtin_amdgcn_sched_barrier(0);
; #pragma unroll
;             for (int db = 0; db < NDB; ++db) o[db] = __builtin_amdgcn_mfma_f32_32x32x16_bf16(va[db], p0.b, o[db], 0, 0, 0);
;             AT_EXP(s0, 8, p1);
;             __builtin_amdgcn_sched_barrier(0);
; #pragma unroll
;             for (int db = 0; db < NDB; ++db) o[db] = __builtin_amdgcn_mfma_f32_32x32x16_bf16(va[NDB + db], p1.b, o[db], 0, 0, 0);
;             AT_EXP(s1, 0, p2);
;             __builtin_amdgcn_sched_barrier(0);
; #pragma unroll
;             for (int db = 0; db < NDB; ++db) o[db] = __builtin_amdgcn_mfma_f32_32x32x16_bf16(vc[db], p2.b, o[db], 0, 0, 0);
;             AT_EXP(s1, 8, p3);
;             __builtin_amdgcn_sched_barrier(0);
; #pragma unroll
;             for (int db = 0; db < NDB; ++db) o[db] = __builtin_amdgcn_mfma_f32_32x32x16_bf16(vc[NDB + db], p3.b, o[db], 0, 0, 0);
;             __builtin_amdgcn_sched_barrier(0);
;     ...
;             l_run += ls0 + ls1;
.LSPs_pv:
	s_cmp_eq_u32 s79, 0
	s_cbranch_scc1 .LSPs_pure
	s_waitcnt lgkmcnt(4)
	v_mfma_f32_32x32x16_bf16 v[50:65], v[146:149], v[238:241], v[50:65]
	v_exp_f32_e32 v98, v98
	v_exp_f32_e32 v99, v99
	v_mfma_f32_32x32x16_bf16 v[34:49], v[150:153], v[238:241], v[34:49]
	v_exp_f32_e32 v100, v100
	v_exp_f32_e32 v101, v101
	v_mfma_f32_32x32x16_bf16 v[18:33], v[154:157], v[238:241], v[18:33]
	v_exp_f32_e32 v102, v102
	v_exp_f32_e32 v103, v103
	v_add_f32_e32 v228, v98, v100
	v_add_f32_e32 v229, v99, v101
	v_mfma_f32_32x32x16_bf16 v[2:17], v[158:161], v[238:241], v[2:17]
	v_exp_f32_e32 v104, v104
	v_exp_f32_e32 v105, v105
	v_add_f32_e32 v228, v228, v102
	v_add_f32_e32 v229, v229, v103
	v_add3_u32 v236, s99, v183, v187
	ds_read_b128 v[146:149], v236 offset:16384
	ds_read_b128 v[150:153], v236 offset:20480
	ds_read_b128 v[154:157], v236 offset:24576
	ds_read_b128 v[158:161], v236 offset:28672
	s_waitcnt lgkmcnt(4)
	v_mfma_f32_32x32x16_bf16 v[50:65], v[130:133], v[242:245], v[50:65]
	v_exp_f32_e32 v106, v106
	v_exp_f32_e32 v107, v107
	v_add_f32_e32 v228, v228, v104
	v_add_f32_e32 v229, v229, v105
	v_cvt_pk_bf16_f32 v238, v98, v99
	v_lshl_add_u64 v[174:175], v[174:175], 0, s[60:61]
	s_add_i32 s80, s78, 0xffff8000
	s_and_b32 s80, s80, 0x18000
	v_mfma_f32_32x32x16_bf16 v[34:49], v[134:137], v[242:245], v[34:49]
	v_exp_f32_e32 v108, v108
	v_exp_f32_e32 v109, v109
	v_add_f32_e32 v228, v228, v106
	v_add_f32_e32 v229, v229, v107
	v_cvt_pk_bf16_f32 v239, v100, v101
	v_lshl_add_u64 v[172:173], v[172:173], 0, s[48:49]
	s_add_i32 s98, s78, 0x10000
	s_and_b32 s98, s98, 0x18000
	v_mfma_f32_32x32x16_bf16 v[18:33], v[138:141], v[242:245], v[18:33]
	v_exp_f32_e32 v110, v110
	v_exp_f32_e32 v111, v111
	v_add_f32_e32 v228, v228, v108
	v_add_f32_e32 v229, v229, v109
	v_cvt_pk_bf16_f32 v240, v102, v103
	v_lshl_add_u64 v[208:209], v[174:175], 0, s[40:41]
	s_add_i32 s98, s98, s29
	s_add_i32 s101, s78, 0x8000
	v_mfma_f32_32x32x16_bf16 v[2:17], v[142:145], v[242:245], v[2:17]
	v_exp_f32_e32 v112, v112
	v_exp_f32_e32 v113, v113
	v_add_f32_e32 v228, v228, v110
	v_add_f32_e32 v229, v229, v111
	v_cvt_pk_bf16_f32 v241, v104, v105
	v_lshl_add_u64 v[210:211], v[172:173], 0, s[40:41]
	s_and_b32 s101, s101, 0x18000
	s_add_i32 s101, s101, s29
	v_add3_u32 v237, s99, v190, v187
	ds_read_b128 v[130:133], v237 offset:16384
	ds_read_b128 v[134:137], v237 offset:20480
	ds_read_b128 v[138:141], v237 offset:24576
	ds_read_b128 v[142:145], v237 offset:28672
	s_waitcnt lgkmcnt(4)
	v_mfma_f32_32x32x16_bf16 v[50:65], v[146:149], v[246:249], v[50:65]
	v_exp_f32_e32 v82, v82
	v_exp_f32_e32 v83, v83
	v_add_f32_e32 v228, v228, v112
	v_add_f32_e32 v229, v229, v113
	v_cvt_pk_bf16_f32 v242, v106, v107
	v_add3_u32 v212, s80, v178, v162
	s_add_i32 s99, s76, 64
	s_cmp_gt_u32 s99, s28
	v_mfma_f32_32x32x16_bf16 v[34:49], v[150:153], v[246:249], v[34:49]
	v_exp_f32_e32 v84, v84
	v_exp_f32_e32 v85, v85
	v_add_f32_e32 v228, v228, v82
	v_add_f32_e32 v229, v229, v83
	v_cvt_pk_bf16_f32 v243, v108, v109
	v_add3_u32 v213, s80, v180, v162
	s_cselect_b32 m0, s31, s30
	s_cmp_lt_u32 s99, s33
	v_mfma_f32_32x32x16_bf16 v[18:33], v[154:157], v[246:249], v[18:33]
	v_exp_f32_e32 v86, v86
	v_exp_f32_e32 v87, v87
	v_add_f32_e32 v228, v228, v84
	v_add_f32_e32 v229, v229, v85
	v_cvt_pk_bf16_f32 v244, v110, v111
	v_add3_u32 v214, s80, v182, v162
	s_cselect_b32 s65, 1, 0
	s_cmp_gt_i32 s99, s67
	v_mfma_f32_32x32x16_bf16 v[2:17], v[158:161], v[246:249], v[2:17]
	v_exp_f32_e32 v88, v88
	v_exp_f32_e32 v89, v89
	v_add_f32_e32 v228, v228, v86
	v_add_f32_e32 v229, v229, v87
	v_cvt_pk_bf16_f32 v245, v112, v113
	v_add3_u32 v215, s80, v184, v162
	s_cselect_b32 s65, s65, 0
	s_cmp_lg_u32 s65, 0
	s_waitcnt lgkmcnt(0)
	v_mfma_f32_32x32x16_bf16 v[50:65], v[130:133], v[250:253], v[50:65]
	v_exp_f32_e32 v90, v90
	v_exp_f32_e32 v91, v91
	v_add_f32_e32 v228, v228, v88
	v_add_f32_e32 v229, v229, v89
	v_cvt_pk_bf16_f32 v246, v82, v83
	s_cselect_b32 m0, 0, m0
	s_add_i32 s99, s78, 0xffff0000
	v_mfma_f32_32x32x16_bf16 v[34:49], v[134:137], v[250:253], v[34:49]
	v_exp_f32_e32 v92, v92
	v_exp_f32_e32 v93, v93
	v_add_f32_e32 v228, v228, v90
	v_add_f32_e32 v229, v229, v91
	v_cvt_pk_bf16_f32 v247, v84, v85
	s_and_b32 s99, s99, 0x18000
	v_mfma_f32_32x32x16_bf16 v[18:33], v[138:141], v[250:253], v[18:33]
	v_exp_f32_e32 v94, v94
	v_exp_f32_e32 v95, v95
	v_add_f32_e32 v228, v228, v92
	v_add_f32_e32 v229, v229, v93
	v_cvt_pk_bf16_f32 v248, v86, v87
	v_mfma_f32_32x32x16_bf16 v[2:17], v[142:145], v[250:253], v[2:17]
	v_exp_f32_e32 v96, v96
	v_exp_f32_e32 v97, v97
	v_add_f32_e32 v228, v228, v94
	v_add_f32_e32 v229, v229, v95
	v_cvt_pk_bf16_f32 v249, v88, v89
	v_add_f32_e32 v228, v228, v96
	v_add_f32_e32 v229, v229, v97
	v_cvt_pk_bf16_f32 v250, v90, v91
	v_cvt_pk_bf16_f32 v251, v92, v93
	v_cvt_pk_bf16_f32 v252, v94, v95
	v_cvt_pk_bf16_f32 v253, v96, v97
	ds_read_b128 v[130:133], v212
	ds_read_b128 v[134:137], v212 offset:4096
	ds_read_b128 v[138:141], v213
	ds_read_b128 v[142:145], v213 offset:4096
	ds_read_b128 v[146:149], v214
	ds_read_b128 v[150:153], v214 offset:4096
	ds_read_b128 v[158:161], v215
	ds_read_b128 v[204:207], v215 offset:4096
	v_add_f32_e32 v228, v228, v229
	v_cmp_nge_f32_e32 vcc, 0x53800000, v228
	s_cbranch_vccnz .LSPs_redo
	s_add_i32 s79, s79, 1
	s_add_i32 s78, s78, 0x8000
	s_addk_i32 s77, 0x100
	s_add_i32 s76, s76, 64
	v_add_f32_e32 v0, v0, v228
	s_cmpk_eq_i32 s77, 0x2000
	s_cbranch_scc0 .LSPs_top
	s_branch .LSPs_exit
; #define ALAS __attribute__((address_space(3)))
; template <bool WIN> ...
;     ...
;             union PFU { u32x4 u; bf16x8 b; };
;             PFU p0, p1, p2, p3;
;             AT_EXP(s0, 0, p0);
; #pragma unroll
;             for (int kk = 0; kk < 2; ++kk)
; #pragma unroll
;                 for (int db = 0; db < NDB; ++db) vc[kk * NDB + db] = *(const ALAS bf16x8*)(sb + vx[kk + 2] + db * 4096);
;             __builtin_amdgcn_sched_barrier(0);
; #pragma unroll
;             for (int db = 0; db < NDB; ++db) o[db] = __builtin_amdgcn_mfma_f32_32x32x16_bf16(va[db], p0.b, o[db], 0, 0, 0);
;             AT_EXP(s0, 8, p1);
;             __builtin_amdgcn_sched_barrier(0);
; #pragma unroll
;             for (int db = 0; db < NDB; ++db) o[db] = __builtin_amdgcn_mfma_f32_32x32x16_bf16(va[NDB + db], p1.b, o[db], 0, 0, 0);
;             AT_EXP(s1, 0, p2);
;             __builtin_amdgcn_sched_barrier(0);
; #pragma unroll
;             for (int db = 0; db < NDB; ++db) o[db] = __builtin_amdgcn_mfma_f32_32x32x16_bf16(vc[db], p2.b, o[db], 0, 0, 0);
;             AT_EXP(s1, 8, p3);
;             __builtin_amdgcn_sched_barrier(0);
; #pragma unroll
;             for (int db = 0; db < NDB; ++db) o[db] = __builtin_amdgcn_mfma_f32_32x32x16_bf16(vc[NDB + db], p3.b, o[db], 0, 0, 0);
;             __builtin_amdgcn_sched_barrier(0);
;     ...
;             l_run += ls0 + ls1;
.LSPs_pure:
	v_lshl_add_u64 v[174:175], v[174:175], 0, s[60:61]
	v_lshl_add_u64 v[172:173], v[172:173], 0, s[48:49]
	s_add_i32 s98, s78, 0x10000
	s_and_b32 s98, s98, 0x18000
	s_add_i32 s98, s98, s29
	s_add_i32 s101, s78, 0x8000
	s_and_b32 s101, s101, 0x18000
	s_add_i32 s101, s101, s29
	v_lshl_add_u64 v[208:209], v[174:175], 0, s[40:41]
	v_lshl_add_u64 v[210:211], v[172:173], 0, s[40:41]
	s_add_i32 s80, s78, 0xffff8000
	s_and_b32 s80, s80, 0x18000
	v_add3_u32 v212, s80, v178, v162
	v_add3_u32 v213, s80, v180, v162
	v_add3_u32 v214, s80, v182, v162
	v_add3_u32 v215, s80, v184, v162
	s_add_i32 s99, s76, 64
	s_cmp_gt_u32 s99, s28
	s_cselect_b32 m0, s31, s30
	s_cmp_lt_u32 s99, s33
	s_cselect_b32 s65, 1, 0
	s_cmp_gt_i32 s99, s67
	s_cselect_b32 s65, s65, 0
	s_cmp_lg_u32 s65, 0
	s_cselect_b32 m0, 0, m0
	s_add_i32 s99, s78, 0xffff0000
	s_and_b32 s99, s99, 0x18000
	v_exp_f32_e32 v98, v98
	v_exp_f32_e32 v99, v99
	v_exp_f32_e32 v100, v100
	v_exp_f32_e32 v101, v101
	v_exp_f32_e32 v102, v102
	v_exp_f32_e32 v103, v103
	v_exp_f32_e32 v104, v104
	v_exp_f32_e32 v105, v105
	v_cvt_pk_bf16_f32 v238, v98, v99
	v_cvt_pk_bf16_f32 v239, v100, v101
	v_cvt_pk_bf16_f32 v240, v102, v103
	v_cvt_pk_bf16_f32 v241, v104, v105
	v_mov_b32_e32 v228, v98
	v_mov_b32_e32 v229, v102
	v_add_f32_e32 v228, v228, v99
	v_add_f32_e32 v229, v229, v103
	v_add_f32_e32 v228, v228, v100
	v_add_f32_e32 v229, v229, v104
	v_add_f32_e32 v228, v228, v101
	v_add_f32_e32 v229, v229, v105
	v_exp_f32_e32 v106, v106
	v_exp_f32_e32 v107, v107
	v_exp_f32_e32 v108, v108
	v_exp_f32_e32 v109, v109
	v_exp_f32_e32 v110, v110
	v_exp_f32_e32 v111, v111
	v_exp_f32_e32 v112, v112
	v_exp_f32_e32 v113, v113
	v_cvt_pk_bf16_f32 v242, v106, v107
	v_cvt_pk_bf16_f32 v243, v108, v109
	v_cvt_pk_bf16_f32 v244, v110, v111
	v_cvt_pk_bf16_f32 v245, v112, v113
	v_add_f32_e32 v228, v228, v106
	v_add_f32_e32 v229, v229, v110
	v_add_f32_e32 v228, v228, v107
	v_add_f32_e32 v229, v229, v111
	v_add_f32_e32 v228, v228, v108
	v_add_f32_e32 v229, v229, v112
	v_add_f32_e32 v228, v228, v109
	v_add_f32_e32 v229, v229, v113
	v_exp_f32_e32 v82, v82
	v_exp_f32_e32 v83, v83
	v_exp_f32_e32 v84, v84
	v_exp_f32_e32 v85, v85
	v_exp_f32_e32 v86, v86
	v_exp_f32_e32 v87, v87
	v_exp_f32_e32 v88, v88
	v_exp_f32_e32 v89, v89
	v_cvt_pk_bf16_f32 v246, v82, v83
	v_cvt_pk_bf16_f32 v247, v84, v85
	v_cvt_pk_bf16_f32 v248, v86, v87
	v_cvt_pk_bf16_f32 v249, v88, v89
	v_add_f32_e32 v228, v228, v82
	v_add_f32_e32 v229, v229, v86
	v_add_f32_e32 v228, v228, v83
	v_add_f32_e32 v229, v229, v87
	v_add_f32_e32 v228, v228, v84
	v_add_f32_e32 v229, v229, v88
	v_add_f32_e32 v228, v228, v85
	v_add_f32_e32 v229, v229, v89
	v_exp_f32_e32 v90, v90
	v_exp_f32_e32 v91, v91
	v_exp_f32_e32 v92, v92
	v_exp_f32_e32 v93, v93
	v_exp_f32_e32 v94, v94
	v_exp_f32_e32 v95, v95
	v_exp_f32_e32 v96, v96
	v_exp_f32_e32 v97, v97
	v_cvt_pk_bf16_f32 v250, v90, v91
	v_cvt_pk_bf16_f32 v251, v92, v93
	v_cvt_pk_bf16_f32 v252, v94, v95
	v_cvt_pk_bf16_f32 v253, v96, v97
	v_add_f32_e32 v228, v228, v90
	v_add_f32_e32 v229, v229, v94
	v_add_f32_e32 v228, v228, v91
	v_add_f32_e32 v229, v229, v95
	v_add_f32_e32 v228, v228, v92
	v_add_f32_e32 v229, v229, v96
	v_add_f32_e32 v228, v228, v93
	v_add_f32_e32 v229, v229, v97
	ds_read_b128 v[130:133], v212
	ds_read_b128 v[134:137], v212 offset:4096
	ds_read_b128 v[138:141], v213
	ds_read_b128 v[142:145], v213 offset:4096
	ds_read_b128 v[146:149], v214
	ds_read_b128 v[150:153], v214 offset:4096
	ds_read_b128 v[158:161], v215
	ds_read_b128 v[204:207], v215 offset:4096
	v_add_f32_e32 v228, v228, v229
	v_cmp_nge_f32_e32 vcc, 0x53800000, v228
	s_cbranch_vccnz .LSPs_redo
	s_add_i32 s79, s79, 1
	s_add_i32 s78, s78, 0x8000
	s_addk_i32 s77, 0x100
	s_add_i32 s76, s76, 64
	v_add_f32_e32 v0, v0, v228
	s_cmpk_eq_i32 s77, 0x2000
	s_cbranch_scc0 .LSPs_top
	s_branch .LSPs_exit

; #define ALAS __attribute__((address_space(3)))
; template <bool WIN> ...
;     ...
;             union PFU { u32x4 u; bf16x8 b; };
;             PFU p0, p1, p2, p3;
;             AT_EXP(s0, 0, p0);
; #pragma unroll
;             for (int kk = 0; kk < 2; ++kk)
; #pragma unroll
;                 for (int db = 0; db < NDB; ++db) vc[kk * NDB + db] = *(const ALAS bf16x8*)(sb + vx[kk + 2] + db * 4096);
;             __builtin_amdgcn_sched_barrier(0);
; #pragma unroll
;             for (int db = 0; db < NDB; ++db) o[db] = __builtin_amdgcn_mfma_f32_32x32x16_bf16(va[db], p0.b, o[db], 0, 0, 0);
;             AT_EXP(s0, 8, p1);
;             __builtin_amdgcn_sched_barrier(0);
; #pragma unroll
;             for (int db = 0; db < NDB; ++db) o[db] = __builtin_amdgcn_mfma_f32_32x32x16_bf16(va[NDB + db], p1.b, o[db], 0, 0, 0);
;             AT_EXP(s1, 0, p2);
;             __builtin_amdgcn_sched_barrier(0);
; #pragma unroll
;             for (int db = 0; db < NDB; ++db) o[db] = __builtin_amdgcn_mfma_f32_32x32x16_bf16(vc[db], p2.b, o[db], 0, 0, 0);
;             AT_EXP(s1, 8, p3);
;             __builtin_amdgcn_sched_barrier(0);
; #pragma unroll
;             for (int db = 0; db < NDB; ++db) o[db] = __builtin_amdgcn_mfma_f32_32x32x16_bf16(vc[NDB + db], p3.b, o[db], 0, 0, 0);
;             __builtin_amdgcn_sched_barrier(0);
;     ...
;             l_run += ls0 + ls1;
.LSPs_pure2:
	s_add_i32 s80, s78, 0xffff8000
	s_and_b32 s80, s80, 0x18000
	v_lshl_add_u64 v[208:209], v[174:175], 0, s[40:41]
	v_lshl_add_u64 v[210:211], v[172:173], 0, s[40:41]
	v_add3_u32 v212, s80, v178, v162
	v_add3_u32 v213, s80, v180, v162
	v_add3_u32 v214, s80, v182, v162
	v_add3_u32 v215, s80, v184, v162
	v_exp_f32_e32 v98, v98
	v_exp_f32_e32 v99, v99
	v_exp_f32_e32 v100, v100
	v_exp_f32_e32 v101, v101
	v_exp_f32_e32 v102, v102
	v_exp_f32_e32 v103, v103
	v_exp_f32_e32 v104, v104
	v_exp_f32_e32 v105, v105
	v_cvt_pk_bf16_f32 v238, v98, v99
	v_cvt_pk_bf16_f32 v239, v100, v101
	v_cvt_pk_bf16_f32 v240, v102, v103
	v_cvt_pk_bf16_f32 v241, v104, v105
	v_mov_b32_e32 v228, v98
	v_mov_b32_e32 v229, v102
	v_add_f32_e32 v228, v228, v99
	v_add_f32_e32 v229, v229, v103
	v_add_f32_e32 v228, v228, v100
	v_add_f32_e32 v229, v229, v104
	v_add_f32_e32 v228, v228, v101
	v_add_f32_e32 v229, v229, v105
	v_exp_f32_e32 v106, v106
	v_exp_f32_e32 v107, v107
	v_exp_f32_e32 v108, v108
	v_exp_f32_e32 v109, v109
	v_exp_f32_e32 v110, v110
	v_exp_f32_e32 v111, v111
	v_exp_f32_e32 v112, v112
	v_exp_f32_e32 v113, v113
	v_cvt_pk_bf16_f32 v242, v106, v107
	v_cvt_pk_bf16_f32 v243, v108, v109
	v_cvt_pk_bf16_f32 v244, v110, v111
	v_cvt_pk_bf16_f32 v245, v112, v113
	v_add_f32_e32 v228, v228, v106
	v_add_f32_e32 v229, v229, v110
	v_add_f32_e32 v228, v228, v107
	v_add_f32_e32 v229, v229, v111
	v_add_f32_e32 v228, v228, v108
	v_add_f32_e32 v229, v229, v112
	v_add_f32_e32 v228, v228, v109
	v_add_f32_e32 v229, v229, v113
	v_exp_f32_e32 v82, v82
	v_exp_f32_e32 v83, v83
	v_exp_f32_e32 v84, v84
	v_exp_f32_e32 v85, v85
	v_exp_f32_e32 v86, v86
	v_exp_f32_e32 v87, v87
	v_exp_f32_e32 v88, v88
	v_exp_f32_e32 v89, v89
	v_cvt_pk_bf16_f32 v246, v82, v83
	v_cvt_pk_bf16_f32 v247, v84, v85
	v_cvt_pk_bf16_f32 v248, v86, v87
	v_cvt_pk_bf16_f32 v249, v88, v89
	v_add_f32_e32 v228, v228, v82
	v_add_f32_e32 v229, v229, v86
	v_add_f32_e32 v228, v228, v83
	v_add_f32_e32 v229, v229, v87
	v_add_f32_e32 v228, v228, v84
	v_add_f32_e32 v229, v229, v88
	v_add_f32_e32 v228, v228, v85
	v_add_f32_e32 v229, v229, v89
	v_exp_f32_e32 v90, v90
	v_exp_f32_e32 v91, v91
	v_exp_f32_e32 v92, v92
	v_exp_f32_e32 v93, v93
	v_exp_f32_e32 v94, v94
	v_exp_f32_e32 v95, v95
	v_exp_f32_e32 v96, v96
	v_exp_f32_e32 v97, v97
	v_cvt_pk_bf16_f32 v250, v90, v91
	v_cvt_pk_bf16_f32 v251, v92, v93
	v_cvt_pk_bf16_f32 v252, v94, v95
	v_cvt_pk_bf16_f32 v253, v96, v97
	v_add_f32_e32 v228, v228, v90
	v_add_f32_e32 v229, v229, v94
	v_add_f32_e32 v228, v228, v91
	v_add_f32_e32 v229, v229, v95
	v_add_f32_e32 v228, v228, v92
	v_add_f32_e32 v229, v229, v96
	v_add_f32_e32 v228, v228, v93
	v_add_f32_e32 v229, v229, v97
	ds_read_b128 v[130:133], v212
	ds_read_b128 v[134:137], v212 offset:4096
	ds_read_b128 v[138:141], v213
	ds_read_b128 v[142:145], v213 offset:4096
	ds_read_b128 v[146:149], v214
	ds_read_b128 v[150:153], v214 offset:4096
	ds_read_b128 v[158:161], v215
	ds_read_b128 v[204:207], v215 offset:4096
	v_add_f32_e32 v228, v228, v229
	s_add_i32 s79, s79, 1
	s_add_i32 s78, s78, 0x8000
	s_addk_i32 s77, 0x100
	s_add_i32 s76, s76, 64
	v_add_f32_e32 v0, v0, v228
	s_cmpk_eq_i32 s77, 0x2000
	s_cbranch_scc0 .LSPs_top
	s_branch .LSPs_exit
